# down GEMM: CUs 0-87 run their split-K tail unit first, then the main unit (staggered residual epilogues)
# baseline (speedup 1.0000x reference)
;     __device__ __forceinline__ bool next(int i, Unit& u) const {
;         long L = (long)i * G + c; const int nwg = nM * nN; u.ui = i;
;         if (L < nwg) {
;             int wgid = (int)L; { const int q = nwg / 8, r = nwg % 8, xcd = wgid % 8, off = wgid / 8; wgid = (xcd < r ? xcd * (q + 1) : r * (q + 1) + (xcd - r) * q) + off; }
;             const int nig = 8 * nN, gid = wgid / nig, fm = gid * 8, gsz = (nM - fm) < 8 ? (nM - fm) : 8;
;             u.pm = fm + ((wgid % nig) % gsz); u.pn = (wgid % nig) / gsz; u.kc = -1; u.nt = ntMain;
;             u.A = A + (size_t)u.pm * 256 * lda + (size_t)(u.pn >> 1) * apn; u.B = B + (size_t)u.pn * 256 * ldb; return true;
;         }
;         L -= nwg; if (L >= (long)nN * nTailK) return false;
;         u.pn = (int)(L % nN); u.kc = (int)(L / nN); u.pm = 32; u.nt = ntTail;
;         u.A = A + (size_t)32 * 256 * lda + (size_t)(u.pn >> 1) * apn + (size_t)u.kc * ntTail * 128; u.B = B + (size_t)u.pn * 256 * ldb + (size_t)u.kc * ntTail * 128; return true;
.LBB0_2365:
	s_or_b64 exec, exec, s[2:3]
	s_mul_i32 s3, s72, 0x1600000
	v_readlane_b32 s4, v255, 28
	s_mul_hi_u32 s2, s72, 0x1600000
	s_add_u32 s28, s4, s3
	v_readlane_b32 s3, v255, 29
	s_addc_u32 s29, s3, s2
	v_readlane_b32 s30, v254, 1
	v_readlane_b32 s31, v254, 0
	v_mov_b32_e32 v10, v1
	s_waitcnt lgkmcnt(0)
	s_barrier
	s_mov_b32 s97, s31
	s_cmpk_lg_i32 s30, 0x100
	s_cbranch_scc1 .Ltf_a_down
	s_cmpk_gt_u32 s31, 87
	s_cbranch_scc1 .Ltf_a_down
	s_add_i32 s97, s31, 0x100
.Ltf_a_down:
	s_cmpk_gt_i32 s97, 0xff
	v_readfirstlane_b32 s10, v10
	s_mov_b64 s[6:7], -1
	s_cbranch_scc0 .LBB0_2368
	s_mov_b64 s[6:7], 0
	s_cmpk_gt_u32 s97, 0x157
	s_mov_b64 s[2:3], 0
	s_cbranch_scc1 .LBB0_2368
	s_lshl_b32 s2, s97, 7
	s_and_b32 s82, s97, 7
	s_and_b32 s2, s2, 0x3c00
	v_readlane_b32 s3, v255, 30
	s_add_u32 s4, s3, s2
	v_readlane_b32 s3, v255, 31
	s_addc_u32 s5, s3, 0
	s_mul_i32 s3, s82, 0x2c0000
	s_add_u32 s3, s28, s3
	s_addc_u32 s8, s29, 0
	s_add_u32 s22, s3, s2
	s_addc_u32 s23, s8, 0
	s_mov_b32 s69, 32
	s_mov_b32 s94, 8
	s_mov_b64 s[2:3], -1

;     __device__ __forceinline__ bool next(int i, Unit& u) const {
;     ...
;             int wgid = (int)L; { const int q = nwg / 8, r = nwg % 8, xcd = wgid % 8, off = wgid / 8; wgid = (xcd < r ? xcd * (q + 1) : r * (q + 1) + (xcd - r) * q) + off; }
;             const int nig = 8 * nN, gid = wgid / nig, fm = gid * 8, gsz = (nM - fm) < 8 ? (nM - fm) : 8;
;             u.pm = fm + ((wgid % nig) % gsz); u.pn = (wgid % nig) / gsz; u.kc = -1; u.nt = ntMain;
;             u.A = A + (size_t)u.pm * 256 * lda + (size_t)(u.pn >> 1) * apn; u.B = B + (size_t)u.pn * 256 * ldb; return true;
.LBB0_2371:
	s_ashr_i32 s2, s97, 31
	s_lshr_b32 s2, s2, 29
	s_add_i32 s4, s97, s2
	s_and_b32 s2, s4, -8
	s_sub_i32 s5, s97, s2
	s_cmp_gt_i32 s5, -1
	s_mov_b64 s[2:3], -1
	s_cbranch_scc0 .LBB0_2373
	s_lshl_b32 s6, s5, 5
	s_mov_b64 s[2:3], 0

;     __device__ __forceinline__ bool next(int i, Unit& u) const {
;         long L = (long)i * G + c; const int nwg = nM * nN; u.ui = i;
;         if (L < nwg) {
;             int wgid = (int)L; { const int q = nwg / 8, r = nwg % 8, xcd = wgid % 8, off = wgid / 8; wgid = (xcd < r ? xcd * (q + 1) : r * (q + 1) + (xcd - r) * q) + off; }
;             const int nig = 8 * nN, gid = wgid / nig, fm = gid * 8, gsz = (nM - fm) < 8 ? (nM - fm) : 8;
;             u.pm = fm + ((wgid % nig) % gsz); u.pn = (wgid % nig) / gsz; u.kc = -1; u.nt = ntMain;
;             u.A = A + (size_t)u.pm * 256 * lda + (size_t)(u.pn >> 1) * apn; u.B = B + (size_t)u.pn * 256 * ldb; return true;
;         }
;         L -= nwg; if (L >= (long)nN * nTailK) return false;
; template <class Epi>
; __device__ __forceinline__ void gemm_phase(LAS unsigned char* lds, const Sched& S, const Epi& E) {
;     ...
;         const bool has_next = S.next(ui + 1, nxt);
.LBB0_2381:
	s_add_i32 s59, s59, 1
	s_mul_i32 s18, s59, s64
	s_mul_hi_u32 s19, s59, s30
	s_add_i32 s19, s19, s18
	s_mul_i32 s18, s59, s30
	s_add_u32 s24, s18, s31
	s_addc_u32 s25, s19, s65
	s_cmpk_lg_i32 s30, 0x100
	s_cbranch_scc1 .Ltf_b_down
	s_cmpk_gt_u32 s31, 87
	s_cbranch_scc1 .Ltf_b_down
	s_cmp_eq_u32 s59, 1
	s_cbranch_scc0 .Ltf_b_down
	s_mov_b32 s24, s31
	s_mov_b32 s25, 0
.Ltf_b_down:
	v_cmp_gt_i64_e32 vcc, s[24:25], v[170:171]
	s_mov_b64 s[26:27], -1
	s_cbranch_vccz .LBB0_2384
	s_add_u32 s18, s24, 0xffffff00
	s_addc_u32 s19, s25, -1
	v_cmp_gt_u64_e32 vcc, s[18:19], v[174:175]
	s_mov_b64 s[26:27], 0
	s_mov_b64 s[18:19], 0
	s_cbranch_vccnz .LBB0_2384
	s_lshl_b32 s14, s24, 7
	s_and_b32 s66, s24, 7
	s_and_b32 s16, s14, 0x3c00
	v_readlane_b32 s14, v255, 30
	s_add_u32 s14, s14, s16
	v_readlane_b32 s15, v255, 31
	s_addc_u32 s15, s15, 0
	s_mul_i32 s17, s66, 0x2c0000
	s_add_u32 s17, s28, s17
	s_addc_u32 s18, s29, 0
	s_add_u32 s16, s17, s16
	s_addc_u32 s17, s18, 0
	s_mov_b32 s67, 32
	s_mov_b32 s68, 8
	s_mov_b64 s[18:19], -1
